# D attention units: one static s_setprio 1 for waves 4-7 at unit-loop entry, reset to 0 at exit
# speedup vs baseline: 1.0054x; 1.0054x over previous
; #define LAS __attribute__((address_space(3)))
; #define GAS __attribute__((address_space(1)))
; DI unsigned char* ARGWS(const Ctx& C) { return (unsigned char*)ARGP(C, 22); }
; DI void attn_unit_d32(const Ctx& C, const bf16_t* __restrict__ Z, bf16_t* __restrict__ Y, int b, int qsel, int hsel, bool ctxq, float lam, float post_scale, const float* subln, const float mref) {
;     constexpr int KST = 136, VST = 72, AT_VT = 64 * 136 * 2;
;     const int tid = C.tid, lane = C.lane, w = C.wave, l31 = lane & 31, hh = lane >> 5, sm = w >> 2, qg = w & 3;
;     const int qrow = (ctxq ? NLAT + 256 * b : b * SEQ) + 128 * qsel + 32 * qg + l31;
;     const int qcol = Z_DQ + 128 * hsel + 64 * sm, kcol = Z_DK + 128 * hsel, vcol = Z_DV + 128 * hsel, ycol = 1536 + 128 * hsel;
;     const int nt = ctxq ? 4 : 36;
;     LAS bf16_t* lds16 = (LAS bf16_t*)C.lds;
;     bf16x8 qf[4];
; #pragma unroll
;     for (int ks = 0; ks < 4; ++ks) qf[ks] = *(const GAS bf16x8*)(Z + (size_t)qrow * ZW + qcol + 16 * ks + 8 * hh);
;     const float negm = -mref;
;     f32x16 o[4]; float lsum = 0.f;
; #pragma unroll
;     for (int d = 0; d < 4; ++d)
; #pragma unroll
;         for (int r = 0; r < 16; ++r) o[d][r] = 0.f;
;     u32x4 kA[2], vA[2], kB[2], vB[2];
;     const int krow = tid >> 3, kch = tid & 7, vp2 = 2 * (lane & 31), vhs = lane >> 5;
;     ...
;     const unsigned koff = (unsigned)(krow * ZW + kcol + 8 * kch), voff = (unsigned)(vp2 * ZW + vcol + 8 * (2 * w + vhs));
; DI void phase_mixers(const Ctx& C, int l, bool last) {
;     unsigned char* ws = ARGWS(C);
;     const bf16_t* Z = (const bf16_t*)(ws + WS_Z); bf16_t* Y = (bf16_t*)(ws + WS_Y);
;     const float* misc = (const float*)(ws + WS_MISC);
;     const float lam = misc[l], post = misc[2 + l], mA = misc[8 + 4 * l], mB = misc[9 + 4 * l], mD = misc[10 + 4 * l];
;     const float* sink = ARGP(C, 11) + l * 8; const float* rpb = ARGP(C, 12) + (size_t)l * 8 * 15 * 31; const float* subln = ARGP(C, 16) + l * 128;
;     const bf16_t* cwT = (const bf16_t*)(ws + WS_CWT) + (size_t)l * 4 * 128 * 128; const float* cscale = ARGP(C, 14) + l * 512;
;     const int nC = last ? (NLAT / 64) * 4 : (MROWS / 64) * 4;
;     for (int rep = 0; rep < ((UDUP & 1) ? 2 : 1); ++rep)
;     if (UMASK & 1) for (int u = C.bid; u < 256; u += C.G) { const int b = u >> 6, qb = (u >> 2) & 15, h = u & 3; attn_unit_d32(C, Z, Y, b, qb, h, false, lam, post, subln, mD); }
.LBB0_391:
	s_andn2_b64 vcc, exec, s[0:1]
	s_cbranch_vccnz .LBB0_694
	s_ashr_i32 s85, s84, 31
	v_readlane_b32 s0, v248, 3
	s_cmp_lt_i32 s0, 2
	s_mov_b64 s[0:1], -1
	v_readlane_b32 s81, v249, 63
	v_readlane_b32 s60, v249, 59
	v_readlane_b32 s61, v249, 60
	s_cbranch_scc1 .LBB0_648
	v_readlane_b32 s0, v248, 3
	s_cmp_gt_i32 s0, 2
	s_mov_b64 s[0:1], -1
	s_cbranch_scc0 .LBB0_549
	v_mov_b32_e32 v0, s66
	ds_read_b32 v0, v0
	s_lshl_b32 s0, s84, 7
	s_ashr_i32 s1, s0, 31
	s_mul_i32 s7, s84, 12
	s_mul_hi_i32 s6, s84, 12
	s_waitcnt lgkmcnt(0)
	v_readfirstlane_b32 s30, v0
	v_mov_b32_e32 v0, s96
	ds_read_b32 v0, v0
	s_add_u32 s8, s30, 0x1b800000
	v_ashrrev_i32_e32 v177, 3, v208
	s_movk_i32 s47, 0x100
	s_movk_i32 s41, 0x2000
	s_waitcnt lgkmcnt(0)
	v_readfirstlane_b32 s31, v0
	s_addc_u32 s9, s31, 0
	s_add_u32 s10, s30, 0x17000000
	s_addc_u32 s11, s31, 0
	s_lshl_b64 s[4:5], s[84:85], 2
	s_add_u32 s4, s30, s4
	s_addc_u32 s5, s31, s5
	v_mov_b64_e32 v[2:3], s[4:5]
	s_add_u32 s4, s4, s7
	s_addc_u32 s5, s5, s6
	flat_load_dword v168, v[2:3]
	flat_load_dword v176, v[2:3] offset:8
	v_mov_b64_e32 v[2:3], s[4:5]
	flat_load_dwordx3 v[164:166], v[2:3] offset:32
	v_readlane_b32 s4, v249, 14
	v_readlane_b32 s5, v249, 19
	s_lshl_b64 s[0:1], s[0:1], 2
	v_mov_b32_e32 v0, s4
	ds_read_b32 v0, v0
	v_readlane_b32 s4, v249, 15
	s_mov_b32 s52, 0x3fb8aa3b
	v_readlane_b32 s58, v248, 2
	s_waitcnt lgkmcnt(0)
	v_readfirstlane_b32 s16, v0
	v_mov_b32_e32 v0, s4
	ds_read_b32 v0, v0
	v_readlane_b32 s4, v249, 16
	s_waitcnt lgkmcnt(0)
	v_readfirstlane_b32 s17, v0
	v_mov_b32_e32 v0, s4
	ds_read_b32 v0, v0
	v_readlane_b32 s4, v249, 17
	s_waitcnt lgkmcnt(0)
	v_readfirstlane_b32 s26, v0
	v_mov_b32_e32 v0, s4
	ds_read_b32 v0, v0
	v_readlane_b32 s4, v249, 18
	s_waitcnt lgkmcnt(0)
	v_readfirstlane_b32 s27, v0
	v_mov_b32_e32 v0, s4
	ds_read_b32 v0, v0
	s_waitcnt lgkmcnt(0)
	v_readfirstlane_b32 s4, v0
	v_mov_b32_e32 v0, s5
	ds_read_b32 v0, v0
	s_add_u32 s12, s4, s0
	v_readlane_b32 s0, v249, 20
	s_waitcnt lgkmcnt(0)
	v_readfirstlane_b32 s5, v0
	v_mov_b32_e32 v0, s0
	ds_read_b32 v0, v0
	v_readlane_b32 s0, v249, 21
	s_addc_u32 s13, s5, s1
	s_cmpk_lt_i32 s51, 0x100
	s_cselect_b64 s[4:5], -1, 0
	s_waitcnt lgkmcnt(0)
	v_readfirstlane_b32 s34, v0
	v_mov_b32_e32 v0, s0
	ds_read_b32 v0, v0
	s_movk_i32 s0, 0x1100
	s_cmpk_gt_i32 s51, 0xff
	v_mul_lo_u32 v178, v177, s0
	s_waitcnt lgkmcnt(0)
	v_readfirstlane_b32 s35, v0
	s_waitcnt vmcnt(0)
	v_mov_b32_e32 v169, v168
	v_xor_b32_e32 v4, 0x80000000, v166
	v_mov_b32_e32 v5, v4
	v_mov_b32_e32 v6, v4
	v_mov_b32_e32 v7, v4
	v_mov_b32_e32 v8, v4
	v_mov_b32_e32 v9, v4
	v_mov_b32_e32 v10, v4
	v_mov_b32_e32 v11, v4
	v_mov_b32_e32 v12, v4
	v_mov_b32_e32 v13, v4
	v_mov_b32_e32 v14, v4
	v_mov_b32_e32 v15, v4
	v_mov_b32_e32 v16, v4
	v_mov_b32_e32 v17, v4
	v_mov_b32_e32 v18, v4
	v_mov_b32_e32 v19, v4
	s_cbranch_scc1 .LBB0_412
	v_lshlrev_b32_e32 v21, 3, v206
	v_ashrrev_i32_e32 v20, 5, v206
	v_and_b32_e32 v21, 56, v21
	v_and_b32_e32 v0, 31, v206
	v_lshlrev_b32_e32 v2, 3, v20
	v_or_b32_e32 v22, v178, v21
	v_add_u32_e32 v179, 0xd00, v22
	v_mul_u32_u24_e32 v22, 0x2200, v0
	v_lshl_add_u32 v23, s58, 4, v2
	s_movk_i32 s6, 0xf00
	v_add3_u32 v180, v22, v23, s6
	s_movk_i32 s6, 0x110
	s_ashr_i32 s0, s58, 2
	v_mul_lo_u32 v22, v177, s6
	v_lshlrev_b32_e32 v21, 1, v21
	s_movk_i32 s6, 0x90
	s_lshl_b32 s1, s58, 5
	s_lshl_b32 s18, s0, 6
	v_add3_u32 v181, 0, v22, v21
	v_mul_lo_u32 v21, v23, s6
	s_lshl_b32 s6, s0, 7
	s_and_b32 s1, s1, 0x60
	s_add_i32 s19, s18, 0xb00
	s_add_i32 s6, s6, 0
	v_and_b32_e32 v22, 25, v0
	v_lshrrev_b32_e32 v182, 1, v0
	v_and_b32_e32 v182, 2, v182
	v_or_b32_e32 v22, v22, v182
	v_lshlrev_b32_e32 v182, 1, v0
	v_and_b32_e32 v182, 4, v182
	v_or_b32_e32 v22, v22, v182
	v_lshlrev_b32_e32 v22, 2, v22
	v_lshlrev_b32_e32 v183, 4, v20
	v_or_b32_e32 v187, s1, v0
	s_movk_i32 s1, 0x210
	s_cmp_eq_u32 s0, 1
	v_lshlrev_b32_e32 v166, 2, v20
	v_add3_u32 v182, 0, v21, v22
	v_add_u32_e32 v21, s6, v183
	v_mul_u32_u24_e32 v184, 0x110, v0
	v_add_u32_e32 v22, 0, v2
	v_mul_u32_u24_e32 v185, 0x90, v0
	v_lshlrev_b32_e32 v23, 2, v206
	v_mad_u32_u24 v0, v187, s1, 0
	s_cselect_b64 s[6:7], -1, 0
	s_cmp_lt_u32 s58, 4
	v_ashrrev_i32_e32 v167, 31, v166
	v_ashrrev_i32_e32 v3, 31, v2
	v_xor_b32_e32 v186, 0x80, v23
	s_cselect_b64 s[14:15], -1, 0
	v_lshl_add_u64 v[170:171], v[166:167], 2, s[12:13]
	v_add_u32_e32 v188, v21, v184
	v_add_u32_e32 v189, v183, v185
	v_add_u32_e32 v190, v0, v183
	v_readlane_b32 s100, v249, 53
	s_nop 3
	s_cmp_ge_u32 s100, 4
	s_cbranch_scc0 .Ldprio_done
	s_setprio 1
.Ldprio_done:
	s_mov_b32 s20, s51
	s_branch .LBB0_397

; template <int MODE>
; DI void attn_unit(const Ctx& C, const bf16_t* __restrict__ Z, bf16_t* __restrict__ Y, int b, int qsel, int hsel, bool ctxq,
;                   const float* sinkp, const float* rpb_h, float lam, float post_scale, const float* subln, const float mref) {
;     ...
;     const int tid = C.tid, lane = C.lane, w = C.wave, l15 = lane & 15, quad = lane >> 4;
;     constexpr int QB = MODE == 0 ? 64 : 128;
;     const int qi = MODE == 0 ? 16 * (w & 3) + l15 : 16 * w + l15;
;     const int qrow = (ctxq ? NLAT + 256 * b : b * SEQ) + QB * qsel + qi;
;     int qcol[NS], kcol, vcol, ycol[NS];
;     if (MODE == 0) { const int h0 = 4 * hsel + 2 * (w >> 2); qcol[0] = Z_AQ + 64 * h0; qcol[NS - 1] = Z_AQ + 64 * (h0 + 1); kcol = Z_AK + 64 * hsel; vcol = Z_AV + 64 * hsel; ycol[0] = 64 * h0; ycol[NS - 1] = 64 * (h0 + 1); }
;     else if (MODE == 1) { qcol[0] = Z_BQ + 64 * hsel; kcol = Z_BK + 64 * hsel; vcol = Z_BV + 64 * hsel; ycol[0] = 512 + 64 * hsel; }
;     else { qcol[0] = Z_DQ + 128 * hsel; qcol[NS - 1] = qcol[0] + 64; kcol = Z_DK + 128 * hsel; vcol = Z_DV + 128 * hsel; ycol[0] = 1536 + 128 * hsel; ycol[NS - 1] = ycol[0]; }
;     int lt0 = 0, nlat = 0;
;     if (!ctxq) {
;         if (MODE == 0) { lt0 = max(0, qsel - 2); nlat = min(31, qsel + 2) - lt0 + 1; }
; DI void phase_mixers(const Ctx& C, int l, bool last) {
;     ...
;     const float lam = misc[l], post = misc[2 + l], mA = misc[8 + 4 * l], mB = misc[9 + 4 * l], mD = misc[10 + 4 * l];
;     const float* sink = ARGP(C, 11) + l * 8; const float* rpb = ARGP(C, 12) + (size_t)l * 8 * 15 * 31; const float* subln = ARGP(C, 16) + l * 128;
;     const bf16_t* cwT = (const bf16_t*)(ws + WS_CWT) + (size_t)l * 4 * 128 * 128; const float* cscale = ARGP(C, 14) + l * 512;
;     const int nC = last ? (NLAT / 64) * 4 : (MROWS / 64) * 4;
;     for (int rep = 0; rep < ((UDUP & 1) ? 2 : 1); ++rep)
;     if (UMASK & 1) for (int u = C.bid; u < 256; u += C.G) { const int b = u >> 6, qb = (u >> 2) & 15, h = u & 3; attn_unit_d32(C, Z, Y, b, qb, h, false, lam, post, subln, mD); }
;     for (int rep = 0; rep < ((UDUP & 2) ? 2 : 1); ++rep)
;     if (UMASK & 2) for (int u = C.bid; u < 256; u += C.G) { const int b = u >> 6, qb = (u >> 1) & 31, g = u & 1; attn_unit<0>(C, Z, Y, b, qb, g, false, sink, nullptr, 0.f, 0.f, nullptr, mA); }
.LBB0_412:
	s_setprio 0
	s_lshl_b32 s0, s84, 3
	s_ashr_i32 s1, s0, 31
	s_lshl_b64 s[0:1], s[0:1], 2
	s_add_u32 s54, s16, s0
	s_movk_i32 s0, 0x1100
	v_xor_b32_e32 v20, 0x80000000, v164
	s_waitcnt vmcnt(6)
	v_ashrrev_i32_e32 v132, 4, v206
	v_mul_lo_u32 v0, v206, s0
	v_and_b32_e32 v133, -16, v206
	s_movk_i32 s0, 0x90
	s_addc_u32 s55, s17, s1
	v_mov_b32_e32 v21, v20
	v_mov_b32_e32 v22, v20
	v_mov_b32_e32 v23, v20
	s_andn2_b64 vcc, exec, s[4:5]
	v_lshlrev_b32_e32 v120, 3, v132
	v_lshl_add_u32 v180, s58, 3, v0
	v_mul_lo_u32 v174, v177, s0
	v_lshl_add_u32 v175, v206, 1, 0
	v_lshlrev_b32_e32 v122, 2, v132
	v_add_u32_e32 v179, 0, v133
	s_cbranch_vccnz .LBB0_442
	s_lshl_b32 s0, s58, 4
	v_lshlrev_b32_e32 v2, 3, v206
	v_and_b32_e32 v0, 15, v206
	s_and_b32 s16, s0, 48
	v_and_b32_e32 v2, 56, v2
	v_or_b32_e32 v134, s16, v0
	v_ashrrev_i32_e32 v121, 31, v120
	v_or_b32_e32 v3, v178, v2
	v_mul_u32_u24_e32 v138, 0x90, v0
	v_sub_u32_e32 v0, v122, v0
	v_lshl_add_u64 v[124:125], v[120:121], 1, s[8:9]
	v_add_u32_e32 v121, 0x200, v3
	v_lshlrev_b32_e32 v3, 2, v206
	v_ashrrev_i32_e32 v123, 31, v122
	v_subrev_u32_e32 v0, s16, v0
	s_ashr_i32 s0, s58, 1
	v_lshl_add_u32 v2, v2, 1, 0
	s_mul_i32 s4, s58, 0x480
	v_xor_b32_e32 v136, 64, v3
	v_xor_b32_e32 v137, 0x80, v3
	v_add_u32_e32 v3, 0, v120
	v_lshl_add_u64 v[126:127], v[122:123], 1, s[10:11]
	v_add_u32_e32 v123, 0xffffff41, v0
	v_sub_u32_e32 v0, v134, v122
	s_and_b32 s17, s0, -2
	v_cmp_gt_u32_e64 s[0:1], 16, v206
	v_add_u32_e32 v135, 0x280, v180
	v_add_u32_e32 v139, 0x8c, v0
	s_waitcnt vmcnt(5)
	v_add_u32_e32 v140, v179, v138
	v_add_u32_e32 v141, v3, v138
	v_add_u32_e32 v142, v2, v174
	v_add_u32_e32 v143, s4, v175
	s_mov_b32 s18, s51
	s_branch .LBB0_416
